# v78 + first two GEMM phases of each tile peeled with C=0 on first-touch MFMAs in P1/P6/P7/P8, removing the 128-move accumulator zeroing per tile
# speedup vs baseline: 1.0092x; 1.0028x over previous
.LBB0_327:
	s_ashr_i32 s37, s36, 31
	s_lshl_b64 s[38:39], s[36:37], 19
	s_add_u32 s38, s84, s38
	s_addc_u32 s39, s85, s39
	s_and_b64 s[40:41], s[0:1], exec
	s_cselect_b32 s3, s39, s43
	s_cselect_b32 s8, s38, s42
	s_ashr_i32 s35, s34, 31
	s_lshl_b64 s[40:41], s[34:35], 19
	s_add_u32 s40, s26, s40
	s_addc_u32 s41, s27, s41
	s_and_b64 s[46:47], s[0:1], exec
	s_cselect_b32 s35, s41, s45
	s_cselect_b32 s37, s40, s44
	s_add_u32 s42, s42, 0x40080
	s_addc_u32 s43, s43, 0
	s_add_u32 s71, s44, 0x100
	s_addc_u32 s72, s45, 0
	s_mov_b32 s73, -2
	ds_read_b128 v[154:157], v164
	ds_read_b128 v[168:171], v164 offset:1024
	ds_read_b128 v[172:175], v164 offset:2048
	ds_read_b128 v[176:179], v164 offset:3072
	ds_read_b128 v[180:183], v165
	ds_read_b128 v[184:187], v165 offset:1024
	ds_read_b128 v[188:191], v165 offset:2048
	ds_read_b128 v[196:199], v165 offset:3072
	s_add_u32 s44, s42, 0xfffc0080
	s_addc_u32 s45, s43, -1
	s_cmp_eq_u32 s73, 12
	s_cselect_b32 s47, s3, s45
	s_cselect_b32 s46, s8, s44
	s_cselect_b32 s45, s35, s72
	s_cselect_b32 s44, s37, s71
	v_lshl_add_u64 v[192:193], s[42:43], 0, v[146:147]
	s_add_i32 m0, s17, 0xc000
	ds_read_b128 v[204:207], v166
	ds_read_b128 v[208:211], v166 offset:1024
	ds_read_b128 v[212:215], v166 offset:2048
	ds_read_b128 v[216:219], v166 offset:3072
	ds_read_b128 v[220:223], v166 offset:4096
	ds_read_b128 v[224:227], v166 offset:5120
	ds_read_b128 v[228:231], v166 offset:6144
	ds_read_b128 v[232:235], v166 offset:7168
	global_load_lds_dwordx4 v[192:193], off
	v_lshl_add_u64 v[192:193], s[42:43], 0, v[148:149]
	s_add_i32 m0, s17, 0xe000
	s_nop 0
	global_load_lds_dwordx4 v[192:193], off
	s_waitcnt vmcnt(8)
	s_waitcnt lgkmcnt(0)
	s_barrier
	s_setprio 1
	s_waitcnt lgkmcnt(0)
	v_mfma_f32_16x16x32_bf16 v[124:127], v[154:157], v[204:207], 0
	v_mfma_f32_16x16x32_bf16 v[120:123], v[172:175], v[204:207], 0
	v_mfma_f32_16x16x32_bf16 v[116:119], v[154:157], v[212:215], 0
	v_mfma_f32_16x16x32_bf16 v[112:115], v[172:175], v[212:215], 0
	v_mfma_f32_16x16x32_bf16 v[100:103], v[154:157], v[220:223], 0
	v_mfma_f32_16x16x32_bf16 v[96:99], v[172:175], v[220:223], 0
	v_mfma_f32_16x16x32_bf16 v[84:87], v[154:157], v[228:231], 0
	v_mfma_f32_16x16x32_bf16 v[80:83], v[172:175], v[228:231], 0
	v_mfma_f32_16x16x32_bf16 v[124:127], v[168:171], v[208:211], v[124:127]
	v_mfma_f32_16x16x32_bf16 v[120:123], v[176:179], v[208:211], v[120:123]
	v_mfma_f32_16x16x32_bf16 v[116:119], v[168:171], v[216:219], v[116:119]
	v_mfma_f32_16x16x32_bf16 v[112:115], v[176:179], v[216:219], v[112:115]
	v_mfma_f32_16x16x32_bf16 v[100:103], v[168:171], v[224:227], v[100:103]
	v_mfma_f32_16x16x32_bf16 v[96:99], v[176:179], v[224:227], v[96:99]
	v_mfma_f32_16x16x32_bf16 v[84:87], v[168:171], v[232:235], v[84:87]
	v_mfma_f32_16x16x32_bf16 v[80:83], v[176:179], v[232:235], v[80:83]
	s_setprio 0
	s_setprio 1
	v_mfma_f32_16x16x32_bf16 v[108:111], v[180:183], v[204:207], 0
	v_mfma_f32_16x16x32_bf16 v[104:107], v[188:191], v[204:207], 0
	v_mfma_f32_16x16x32_bf16 v[92:95], v[180:183], v[212:215], 0
	v_mfma_f32_16x16x32_bf16 v[88:91], v[188:191], v[212:215], 0
	v_mfma_f32_16x16x32_bf16 v[76:79], v[180:183], v[220:223], 0
	v_mfma_f32_16x16x32_bf16 v[72:75], v[188:191], v[220:223], 0
	v_mfma_f32_16x16x32_bf16 v[68:71], v[180:183], v[228:231], 0
	v_mfma_f32_16x16x32_bf16 v[64:67], v[188:191], v[228:231], 0
	v_mfma_f32_16x16x32_bf16 v[108:111], v[184:187], v[208:211], v[108:111]
	v_mfma_f32_16x16x32_bf16 v[104:107], v[196:199], v[208:211], v[104:107]
	v_mfma_f32_16x16x32_bf16 v[92:95], v[184:187], v[216:219], v[92:95]
	v_mfma_f32_16x16x32_bf16 v[88:91], v[196:199], v[216:219], v[88:91]
	v_mfma_f32_16x16x32_bf16 v[76:79], v[184:187], v[224:227], v[76:79]
	v_mfma_f32_16x16x32_bf16 v[72:75], v[196:199], v[224:227], v[72:75]
	v_mfma_f32_16x16x32_bf16 v[68:71], v[184:187], v[232:235], v[68:71]
	v_mfma_f32_16x16x32_bf16 v[64:67], v[196:199], v[232:235], v[64:67]
	s_setprio 0
	s_barrier
	s_add_i32 s76, s65, s33
	v_lshl_add_u64 v[192:193], s[44:45], 0, v[132:133]
	s_mov_b32 m0, s76
	ds_read_b128 v[204:207], v166 offset:16384
	ds_read_b128 v[208:211], v166 offset:17408
	ds_read_b128 v[212:215], v166 offset:18432
	ds_read_b128 v[216:219], v166 offset:19456
	ds_read_b128 v[220:223], v166 offset:20480
	ds_read_b128 v[224:227], v166 offset:21504
	ds_read_b128 v[228:231], v166 offset:22528
	ds_read_b128 v[232:235], v166 offset:23552
	global_load_lds_dwordx4 v[192:193], off
	s_add_i32 m0, s76, 0x2000
	s_add_u32 s76, s44, 0x40000
	v_lshl_add_u64 v[200:201], s[44:45], 0, v[136:137]
	s_addc_u32 s77, s45, 0
	s_add_i32 s78, s66, s33
	global_load_lds_dwordx4 v[200:201], off
	v_lshl_add_u64 v[236:237], s[76:77], 0, v[132:133]
	s_mov_b32 m0, s78
	v_lshl_add_u64 v[238:239], s[46:47], 0, v[134:135]
	global_load_lds_dwordx4 v[236:237], off
	v_lshl_add_u64 v[236:237], s[76:77], 0, v[136:137]
	s_add_i32 m0, s78, 0x2000
	s_nop 0
	global_load_lds_dwordx4 v[236:237], off
	v_lshl_add_u64 v[236:237], s[46:47], 0, v[130:131]
	s_mov_b32 m0, s17
	s_nop 0
	global_load_lds_dwordx4 v[236:237], off
	s_mov_b32 m0, s48
	s_nop 0
	global_load_lds_dwordx4 v[238:239], off
	s_waitcnt vmcnt(8)
	s_waitcnt lgkmcnt(0)
	s_barrier
	s_setprio 1
	s_waitcnt lgkmcnt(0)
	v_mfma_f32_16x16x32_bf16 v[60:63], v[154:157], v[204:207], 0
	v_mfma_f32_16x16x32_bf16 v[56:59], v[172:175], v[204:207], 0
	v_mfma_f32_16x16x32_bf16 v[52:55], v[154:157], v[212:215], 0
	v_mfma_f32_16x16x32_bf16 v[48:51], v[172:175], v[212:215], 0
	v_mfma_f32_16x16x32_bf16 v[36:39], v[154:157], v[220:223], 0
	v_mfma_f32_16x16x32_bf16 v[32:35], v[172:175], v[220:223], 0
	v_mfma_f32_16x16x32_bf16 v[20:23], v[154:157], v[228:231], 0
	v_mfma_f32_16x16x32_bf16 v[16:19], v[172:175], v[228:231], 0
	v_mfma_f32_16x16x32_bf16 v[60:63], v[168:171], v[208:211], v[60:63]
	v_mfma_f32_16x16x32_bf16 v[56:59], v[176:179], v[208:211], v[56:59]
	v_mfma_f32_16x16x32_bf16 v[52:55], v[168:171], v[216:219], v[52:55]
	v_mfma_f32_16x16x32_bf16 v[48:51], v[176:179], v[216:219], v[48:51]
	v_mfma_f32_16x16x32_bf16 v[36:39], v[168:171], v[224:227], v[36:39]
	v_mfma_f32_16x16x32_bf16 v[32:35], v[176:179], v[224:227], v[32:35]
	v_mfma_f32_16x16x32_bf16 v[20:23], v[168:171], v[232:235], v[20:23]
	v_mfma_f32_16x16x32_bf16 v[16:19], v[176:179], v[232:235], v[16:19]
	s_setprio 0
	s_setprio 1
	v_mfma_f32_16x16x32_bf16 v[44:47], v[180:183], v[204:207], 0
	v_mfma_f32_16x16x32_bf16 v[40:43], v[188:191], v[204:207], 0
	v_mfma_f32_16x16x32_bf16 v[28:31], v[180:183], v[212:215], 0
	v_mfma_f32_16x16x32_bf16 v[24:27], v[188:191], v[212:215], 0
	v_mfma_f32_16x16x32_bf16 v[12:15], v[180:183], v[220:223], 0
	v_mfma_f32_16x16x32_bf16 v[8:11], v[188:191], v[220:223], 0
	v_mfma_f32_16x16x32_bf16 v[4:7], v[180:183], v[228:231], 0
	v_mfma_f32_16x16x32_bf16 v[0:3], v[188:191], v[228:231], 0
	v_mfma_f32_16x16x32_bf16 v[44:47], v[184:187], v[208:211], v[44:47]
	v_mfma_f32_16x16x32_bf16 v[40:43], v[196:199], v[208:211], v[40:43]
	v_mfma_f32_16x16x32_bf16 v[28:31], v[184:187], v[216:219], v[28:31]
	v_mfma_f32_16x16x32_bf16 v[24:27], v[196:199], v[216:219], v[24:27]
	v_mfma_f32_16x16x32_bf16 v[12:15], v[184:187], v[224:227], v[12:15]
	v_mfma_f32_16x16x32_bf16 v[8:11], v[196:199], v[224:227], v[8:11]
	v_mfma_f32_16x16x32_bf16 v[4:7], v[184:187], v[232:235], v[4:7]
	v_mfma_f32_16x16x32_bf16 v[0:3], v[196:199], v[232:235], v[0:3]
	s_setprio 0
	s_barrier
	s_branch .Lpeel_mid_0

.Lpeel_mid_0:
	s_add_i32 s76, 0, 0x18000
	v_add_u32_e32 v138, s76, v161
	s_add_i32 s77, 0, 0x1c000
	ds_read_b128 v[154:157], v138
	ds_read_b128 v[168:171], v138 offset:1024
	ds_read_b128 v[172:175], v138 offset:2048
	ds_read_b128 v[176:179], v138 offset:3072
	v_add_u32_e32 v138, s77, v161
	ds_read_b128 v[180:183], v138
	ds_read_b128 v[184:187], v138 offset:1024
	ds_read_b128 v[188:191], v138 offset:2048
	ds_read_b128 v[196:199], v138 offset:3072
	s_add_u32 s46, s46, 0x40000
	s_addc_u32 s47, s47, 0
	s_mov_b32 m0, s49
	v_lshl_add_u64 v[240:241], s[46:47], 0, v[130:131]
	ds_read_b128 v[204:207], v166 offset:32768
	ds_read_b128 v[208:211], v166 offset:33792
	ds_read_b128 v[212:215], v166 offset:34816
	ds_read_b128 v[216:219], v166 offset:35840
	ds_read_b128 v[220:223], v166 offset:36864
	ds_read_b128 v[224:227], v166 offset:37888
	ds_read_b128 v[228:231], v166 offset:38912
	ds_read_b128 v[232:235], v166 offset:39936
	global_load_lds_dwordx4 v[240:241], off
	v_lshl_add_u64 v[240:241], s[46:47], 0, v[134:135]
	s_mov_b32 m0, s53
	s_nop 0
	global_load_lds_dwordx4 v[240:241], off
	s_waitcnt vmcnt(8)
	s_waitcnt lgkmcnt(0)
	s_barrier
	s_setprio 1
	s_waitcnt lgkmcnt(0)
	v_mfma_f32_16x16x32_bf16 v[124:127], v[154:157], v[204:207], v[124:127]
	v_mfma_f32_16x16x32_bf16 v[120:123], v[172:175], v[204:207], v[120:123]
	v_mfma_f32_16x16x32_bf16 v[116:119], v[154:157], v[212:215], v[116:119]
	v_mfma_f32_16x16x32_bf16 v[112:115], v[172:175], v[212:215], v[112:115]
	v_mfma_f32_16x16x32_bf16 v[100:103], v[154:157], v[220:223], v[100:103]
	v_mfma_f32_16x16x32_bf16 v[96:99], v[172:175], v[220:223], v[96:99]
	v_mfma_f32_16x16x32_bf16 v[84:87], v[154:157], v[228:231], v[84:87]
	v_mfma_f32_16x16x32_bf16 v[80:83], v[172:175], v[228:231], v[80:83]
	v_mfma_f32_16x16x32_bf16 v[124:127], v[168:171], v[208:211], v[124:127]
	v_mfma_f32_16x16x32_bf16 v[120:123], v[176:179], v[208:211], v[120:123]
	v_mfma_f32_16x16x32_bf16 v[116:119], v[168:171], v[216:219], v[116:119]
	v_mfma_f32_16x16x32_bf16 v[112:115], v[176:179], v[216:219], v[112:115]
	v_mfma_f32_16x16x32_bf16 v[100:103], v[168:171], v[224:227], v[100:103]
	v_mfma_f32_16x16x32_bf16 v[96:99], v[176:179], v[224:227], v[96:99]
	v_mfma_f32_16x16x32_bf16 v[84:87], v[168:171], v[232:235], v[84:87]
	v_mfma_f32_16x16x32_bf16 v[80:83], v[176:179], v[232:235], v[80:83]
	s_setprio 0
	s_setprio 1
	v_mfma_f32_16x16x32_bf16 v[108:111], v[180:183], v[204:207], v[108:111]
	v_mfma_f32_16x16x32_bf16 v[104:107], v[188:191], v[204:207], v[104:107]
	v_mfma_f32_16x16x32_bf16 v[92:95], v[180:183], v[212:215], v[92:95]
	v_mfma_f32_16x16x32_bf16 v[88:91], v[188:191], v[212:215], v[88:91]
	v_mfma_f32_16x16x32_bf16 v[76:79], v[180:183], v[220:223], v[76:79]
	v_mfma_f32_16x16x32_bf16 v[72:75], v[188:191], v[220:223], v[72:75]
	v_mfma_f32_16x16x32_bf16 v[68:71], v[180:183], v[228:231], v[68:71]
	v_mfma_f32_16x16x32_bf16 v[64:67], v[188:191], v[228:231], v[64:67]
	v_mfma_f32_16x16x32_bf16 v[108:111], v[184:187], v[208:211], v[108:111]
	v_mfma_f32_16x16x32_bf16 v[104:107], v[196:199], v[208:211], v[104:107]
	v_mfma_f32_16x16x32_bf16 v[92:95], v[184:187], v[216:219], v[92:95]
	v_mfma_f32_16x16x32_bf16 v[88:91], v[196:199], v[216:219], v[88:91]
	v_mfma_f32_16x16x32_bf16 v[76:79], v[184:187], v[224:227], v[76:79]
	v_mfma_f32_16x16x32_bf16 v[72:75], v[196:199], v[224:227], v[72:75]
	v_mfma_f32_16x16x32_bf16 v[68:71], v[184:187], v[232:235], v[68:71]
	v_mfma_f32_16x16x32_bf16 v[64:67], v[196:199], v[232:235], v[64:67]
	s_setprio 0
	s_barrier
	s_add_i32 s46, s76, s33
	v_lshl_add_u64 v[192:193], v[192:193], 0, s[14:15]
	s_mov_b32 m0, s46
	ds_read_b128 v[204:207], v166 offset:49152
	ds_read_b128 v[208:211], v166 offset:50176
	ds_read_b128 v[212:215], v166 offset:51200
	ds_read_b128 v[216:219], v166 offset:52224
	ds_read_b128 v[220:223], v166 offset:53248
	ds_read_b128 v[224:227], v166 offset:54272
	ds_read_b128 v[228:231], v166 offset:55296
	ds_read_b128 v[232:235], v166 offset:56320
	global_load_lds_dwordx4 v[192:193], off
	s_add_i32 m0, s46, 0x2000
	s_add_u32 s44, s44, 0x40080
	v_lshl_add_u64 v[192:193], v[200:201], 0, s[14:15]
	s_addc_u32 s45, s45, 0
	s_add_i32 s46, s77, s33
	global_load_lds_dwordx4 v[192:193], off
	v_lshl_add_u64 v[192:193], s[44:45], 0, v[132:133]
	s_mov_b32 m0, s46
	s_nop 0
	global_load_lds_dwordx4 v[192:193], off
	v_lshl_add_u64 v[192:193], s[44:45], 0, v[136:137]
	s_add_i32 m0, s46, 0x2000
	s_nop 0
	global_load_lds_dwordx4 v[192:193], off
	v_lshl_add_u64 v[192:193], v[236:237], 0, s[14:15]
	s_mov_b32 m0, s58
	s_nop 0
	global_load_lds_dwordx4 v[192:193], off
	v_lshl_add_u64 v[192:193], v[238:239], 0, s[14:15]
	s_mov_b32 m0, s59
	s_nop 0
	global_load_lds_dwordx4 v[192:193], off
	s_waitcnt vmcnt(8)
	s_waitcnt lgkmcnt(0)
	s_barrier
	s_setprio 1
	s_waitcnt lgkmcnt(0)
	v_mfma_f32_16x16x32_bf16 v[60:63], v[154:157], v[204:207], v[60:63]
	v_mfma_f32_16x16x32_bf16 v[56:59], v[172:175], v[204:207], v[56:59]
	v_mfma_f32_16x16x32_bf16 v[52:55], v[154:157], v[212:215], v[52:55]
	v_mfma_f32_16x16x32_bf16 v[48:51], v[172:175], v[212:215], v[48:51]
	v_mfma_f32_16x16x32_bf16 v[36:39], v[154:157], v[220:223], v[36:39]
	v_mfma_f32_16x16x32_bf16 v[32:35], v[172:175], v[220:223], v[32:35]
	v_mfma_f32_16x16x32_bf16 v[20:23], v[154:157], v[228:231], v[20:23]
	v_mfma_f32_16x16x32_bf16 v[16:19], v[172:175], v[228:231], v[16:19]
	v_mfma_f32_16x16x32_bf16 v[60:63], v[168:171], v[208:211], v[60:63]
	v_mfma_f32_16x16x32_bf16 v[56:59], v[176:179], v[208:211], v[56:59]
	v_mfma_f32_16x16x32_bf16 v[52:55], v[168:171], v[216:219], v[52:55]
	v_mfma_f32_16x16x32_bf16 v[48:51], v[176:179], v[216:219], v[48:51]
	v_mfma_f32_16x16x32_bf16 v[36:39], v[168:171], v[224:227], v[36:39]
	v_mfma_f32_16x16x32_bf16 v[32:35], v[176:179], v[224:227], v[32:35]
	v_mfma_f32_16x16x32_bf16 v[20:23], v[168:171], v[232:235], v[20:23]
	v_mfma_f32_16x16x32_bf16 v[16:19], v[176:179], v[232:235], v[16:19]
	s_setprio 0
	s_setprio 1
	v_mfma_f32_16x16x32_bf16 v[44:47], v[180:183], v[204:207], v[44:47]
	v_mfma_f32_16x16x32_bf16 v[40:43], v[188:191], v[204:207], v[40:43]
	v_mfma_f32_16x16x32_bf16 v[28:31], v[180:183], v[212:215], v[28:31]
	v_mfma_f32_16x16x32_bf16 v[24:27], v[188:191], v[212:215], v[24:27]
	v_mfma_f32_16x16x32_bf16 v[12:15], v[180:183], v[220:223], v[12:15]
	v_mfma_f32_16x16x32_bf16 v[8:11], v[188:191], v[220:223], v[8:11]
	v_mfma_f32_16x16x32_bf16 v[4:7], v[180:183], v[228:231], v[4:7]
	v_mfma_f32_16x16x32_bf16 v[0:3], v[188:191], v[228:231], v[0:3]
	v_mfma_f32_16x16x32_bf16 v[44:47], v[184:187], v[208:211], v[44:47]
	v_mfma_f32_16x16x32_bf16 v[40:43], v[196:199], v[208:211], v[40:43]
	v_mfma_f32_16x16x32_bf16 v[28:31], v[184:187], v[216:219], v[28:31]
	v_mfma_f32_16x16x32_bf16 v[24:27], v[196:199], v[216:219], v[24:27]
	v_mfma_f32_16x16x32_bf16 v[12:15], v[184:187], v[224:227], v[12:15]
	v_mfma_f32_16x16x32_bf16 v[8:11], v[196:199], v[224:227], v[8:11]
	v_mfma_f32_16x16x32_bf16 v[4:7], v[184:187], v[232:235], v[4:7]
	v_mfma_f32_16x16x32_bf16 v[0:3], v[196:199], v[232:235], v[0:3]
	s_setprio 0
	s_barrier
	s_add_i32 s73, s73, 2
	s_add_u32 s42, s42, 0x100
	s_addc_u32 s43, s43, 0
	s_add_u32 s71, s71, 0x100
	s_addc_u32 s72, s72, 0
	s_cmp_gt_u32 s73, 13
	s_cbranch_scc0 .LBB0_328
	s_and_b64 vcc, exec, s[18:19]
	s_cbranch_vccz .LBB0_331
	s_barrier

.LBB0_899:
	s_ashr_i32 s15, s14, 31
	s_lshl_b64 s[16:17], s[14:15], 19
	s_add_u32 s16, s86, s16
	s_addc_u32 s17, s87, s17
	s_and_b64 s[18:19], s[6:7], exec
	s_cselect_b32 s15, s17, s25
	s_cselect_b32 s21, s16, s24
	s_ashr_i32 s13, s12, 31
	s_lshl_b64 s[18:19], s[12:13], 19
	s_add_u32 s18, s80, s18
	s_addc_u32 s19, s81, s19
	s_and_b64 s[28:29], s[6:7], exec
	s_cselect_b32 s13, s19, s27
	s_cselect_b32 s43, s18, s26
	s_add_u32 s24, s24, 0x40080
	s_addc_u32 s25, s25, 0
	s_add_u32 s44, s26, 0x100
	s_addc_u32 s45, s27, 0
	s_mov_b32 s46, -2
	s_waitcnt lgkmcnt(0)
	s_waitcnt vmcnt(0)
	ds_read_b128 v[128:131], v206
	ds_read_b128 v[132:135], v206 offset:1024
	ds_read_b128 v[136:139], v206 offset:2048
	ds_read_b128 v[140:143], v206 offset:3072
	ds_read_b128 v[144:147], v207
	ds_read_b128 v[148:151], v207 offset:1024
	ds_read_b128 v[152:155], v207 offset:2048
	ds_read_b128 v[156:159], v207 offset:3072
	s_add_u32 s26, s24, 0xfffc0080
	s_addc_u32 s27, s25, -1
	s_cmp_eq_u32 s46, 12
	s_cselect_b32 s29, s15, s27
	s_cselect_b32 s28, s21, s26
	s_cselect_b32 s27, s13, s45
	s_cselect_b32 s26, s43, s44
	v_lshl_add_u64 v[200:201], s[24:25], 0, v[180:181]
	s_add_i32 m0, s23, 0xc000
	ds_read_b128 v[160:163], v208
	ds_read_b128 v[164:167], v208 offset:1024
	ds_read_b128 v[168:171], v208 offset:2048
	ds_read_b128 v[172:175], v208 offset:3072
	ds_read_b128 v[188:191], v208 offset:4096
	ds_read_b128 v[192:195], v208 offset:5120
	ds_read_b128 v[196:199], v208 offset:6144
	ds_read_b128 v[210:213], v208 offset:7168
	global_load_lds_dwordx4 v[200:201], off
	v_lshl_add_u64 v[200:201], s[24:25], 0, v[182:183]
	s_add_i32 m0, s23, 0xe000
	s_nop 0
	global_load_lds_dwordx4 v[200:201], off
	s_waitcnt vmcnt(8)
	s_waitcnt lgkmcnt(0)
	s_barrier
	s_setprio 1
	s_waitcnt lgkmcnt(0)
	v_mfma_f32_16x16x32_bf16 v[124:127], v[128:131], v[160:163], 0
	v_mfma_f32_16x16x32_bf16 v[120:123], v[136:139], v[160:163], 0
	v_mfma_f32_16x16x32_bf16 v[108:111], v[128:131], v[168:171], 0
	v_mfma_f32_16x16x32_bf16 v[104:107], v[136:139], v[168:171], 0
	v_mfma_f32_16x16x32_bf16 v[92:95], v[128:131], v[188:191], 0
	v_mfma_f32_16x16x32_bf16 v[88:91], v[136:139], v[188:191], 0
	v_mfma_f32_16x16x32_bf16 v[76:79], v[128:131], v[196:199], 0
	v_mfma_f32_16x16x32_bf16 v[72:75], v[136:139], v[196:199], 0
	v_mfma_f32_16x16x32_bf16 v[124:127], v[132:135], v[164:167], v[124:127]
	v_mfma_f32_16x16x32_bf16 v[120:123], v[140:143], v[164:167], v[120:123]
	v_mfma_f32_16x16x32_bf16 v[108:111], v[132:135], v[172:175], v[108:111]
	v_mfma_f32_16x16x32_bf16 v[104:107], v[140:143], v[172:175], v[104:107]
	v_mfma_f32_16x16x32_bf16 v[92:95], v[132:135], v[192:195], v[92:95]
	v_mfma_f32_16x16x32_bf16 v[88:91], v[140:143], v[192:195], v[88:91]
	v_mfma_f32_16x16x32_bf16 v[76:79], v[132:135], v[210:213], v[76:79]
	v_mfma_f32_16x16x32_bf16 v[72:75], v[140:143], v[210:213], v[72:75]
	s_setprio 0
	s_setprio 1
	v_mfma_f32_16x16x32_bf16 v[116:119], v[144:147], v[160:163], 0
	v_mfma_f32_16x16x32_bf16 v[112:115], v[152:155], v[160:163], 0
	v_mfma_f32_16x16x32_bf16 v[100:103], v[144:147], v[168:171], 0
	v_mfma_f32_16x16x32_bf16 v[96:99], v[152:155], v[168:171], 0
	v_mfma_f32_16x16x32_bf16 v[84:87], v[144:147], v[188:191], 0
	v_mfma_f32_16x16x32_bf16 v[80:83], v[152:155], v[188:191], 0
	v_mfma_f32_16x16x32_bf16 v[68:71], v[144:147], v[196:199], 0
	v_mfma_f32_16x16x32_bf16 v[64:67], v[152:155], v[196:199], 0
	v_mfma_f32_16x16x32_bf16 v[116:119], v[148:151], v[164:167], v[116:119]
	v_mfma_f32_16x16x32_bf16 v[112:115], v[156:159], v[164:167], v[112:115]
	v_mfma_f32_16x16x32_bf16 v[100:103], v[148:151], v[172:175], v[100:103]
	v_mfma_f32_16x16x32_bf16 v[96:99], v[156:159], v[172:175], v[96:99]
	v_mfma_f32_16x16x32_bf16 v[84:87], v[148:151], v[192:195], v[84:87]
	v_mfma_f32_16x16x32_bf16 v[80:83], v[156:159], v[192:195], v[80:83]
	v_mfma_f32_16x16x32_bf16 v[68:71], v[148:151], v[210:213], v[68:71]
	v_mfma_f32_16x16x32_bf16 v[64:67], v[156:159], v[210:213], v[64:67]
	s_setprio 0
	s_barrier
	s_add_i32 s47, s41, s30
	v_lshl_add_u64 v[200:201], s[26:27], 0, v[176:177]
	s_mov_b32 m0, s47
	ds_read_b128 v[160:163], v208 offset:16384
	ds_read_b128 v[164:167], v208 offset:17408
	ds_read_b128 v[168:171], v208 offset:18432
	ds_read_b128 v[172:175], v208 offset:19456
	ds_read_b128 v[188:191], v208 offset:20480
	ds_read_b128 v[192:195], v208 offset:21504
	ds_read_b128 v[196:199], v208 offset:22528
	ds_read_b128 v[210:213], v208 offset:23552
	global_load_lds_dwordx4 v[200:201], off
	s_add_i32 m0, s47, 0x2000
	s_add_u32 s48, s26, 0x40000
	v_lshl_add_u64 v[214:215], s[26:27], 0, v[178:179]
	s_addc_u32 s49, s27, 0
	s_add_i32 s47, s42, s30
	global_load_lds_dwordx4 v[214:215], off
	v_lshl_add_u64 v[216:217], s[48:49], 0, v[176:177]
	s_mov_b32 m0, s47
	v_lshl_add_u64 v[218:219], s[28:29], 0, v[178:179]
	global_load_lds_dwordx4 v[216:217], off
	v_lshl_add_u64 v[216:217], s[48:49], 0, v[178:179]
	s_add_i32 m0, s47, 0x2000
	s_nop 0
	global_load_lds_dwordx4 v[216:217], off
	v_lshl_add_u64 v[216:217], s[28:29], 0, v[176:177]
	s_mov_b32 m0, s23
	s_nop 0
	global_load_lds_dwordx4 v[216:217], off
	s_mov_b32 m0, s31
	s_nop 0
	global_load_lds_dwordx4 v[218:219], off
	s_waitcnt vmcnt(8)
	s_waitcnt lgkmcnt(0)
	s_barrier
	s_setprio 1
	s_waitcnt lgkmcnt(0)
	v_mfma_f32_16x16x32_bf16 v[60:63], v[128:131], v[160:163], 0
	v_mfma_f32_16x16x32_bf16 v[56:59], v[136:139], v[160:163], 0
	v_mfma_f32_16x16x32_bf16 v[44:47], v[128:131], v[168:171], 0
	v_mfma_f32_16x16x32_bf16 v[40:43], v[136:139], v[168:171], 0
	v_mfma_f32_16x16x32_bf16 v[28:31], v[128:131], v[188:191], 0
	v_mfma_f32_16x16x32_bf16 v[24:27], v[136:139], v[188:191], 0
	v_mfma_f32_16x16x32_bf16 v[12:15], v[128:131], v[196:199], 0
	v_mfma_f32_16x16x32_bf16 v[8:11], v[136:139], v[196:199], 0
	v_mfma_f32_16x16x32_bf16 v[60:63], v[132:135], v[164:167], v[60:63]
	v_mfma_f32_16x16x32_bf16 v[56:59], v[140:143], v[164:167], v[56:59]
	v_mfma_f32_16x16x32_bf16 v[44:47], v[132:135], v[172:175], v[44:47]
	v_mfma_f32_16x16x32_bf16 v[40:43], v[140:143], v[172:175], v[40:43]
	v_mfma_f32_16x16x32_bf16 v[28:31], v[132:135], v[192:195], v[28:31]
	v_mfma_f32_16x16x32_bf16 v[24:27], v[140:143], v[192:195], v[24:27]
	v_mfma_f32_16x16x32_bf16 v[12:15], v[132:135], v[210:213], v[12:15]
	v_mfma_f32_16x16x32_bf16 v[8:11], v[140:143], v[210:213], v[8:11]
	s_setprio 0
	s_setprio 1
	v_mfma_f32_16x16x32_bf16 v[52:55], v[144:147], v[160:163], 0
	v_mfma_f32_16x16x32_bf16 v[48:51], v[152:155], v[160:163], 0
	v_mfma_f32_16x16x32_bf16 v[36:39], v[144:147], v[168:171], 0
	v_mfma_f32_16x16x32_bf16 v[32:35], v[152:155], v[168:171], 0
	v_mfma_f32_16x16x32_bf16 v[20:23], v[144:147], v[188:191], 0
	v_mfma_f32_16x16x32_bf16 v[16:19], v[152:155], v[188:191], 0
	v_mfma_f32_16x16x32_bf16 v[4:7], v[144:147], v[196:199], 0
	v_mfma_f32_16x16x32_bf16 v[0:3], v[152:155], v[196:199], 0
	v_mfma_f32_16x16x32_bf16 v[52:55], v[148:151], v[164:167], v[52:55]
	v_mfma_f32_16x16x32_bf16 v[48:51], v[156:159], v[164:167], v[48:51]
	v_mfma_f32_16x16x32_bf16 v[36:39], v[148:151], v[172:175], v[36:39]
	v_mfma_f32_16x16x32_bf16 v[32:35], v[156:159], v[172:175], v[32:35]
	v_mfma_f32_16x16x32_bf16 v[20:23], v[148:151], v[192:195], v[20:23]
	v_mfma_f32_16x16x32_bf16 v[16:19], v[156:159], v[192:195], v[16:19]
	v_mfma_f32_16x16x32_bf16 v[4:7], v[148:151], v[210:213], v[4:7]
	v_mfma_f32_16x16x32_bf16 v[0:3], v[156:159], v[210:213], v[0:3]
	s_setprio 0
	s_barrier
	s_branch .Lpeel_mid_b900

.Lpeel_mid_b900:
	s_add_i32 s47, 0, 0x18000
	s_add_i32 s48, 0, 0x1c000
	v_add_u32_e32 v140, s47, v204
	v_add_u32_e32 v156, s48, v204
	ds_read_b128 v[128:131], v140
	ds_read_b128 v[132:135], v140 offset:1024
	ds_read_b128 v[136:139], v140 offset:2048
	ds_read_b128 v[140:143], v140 offset:3072
	ds_read_b128 v[144:147], v156
	ds_read_b128 v[148:151], v156 offset:1024
	ds_read_b128 v[152:155], v156 offset:2048
	ds_read_b128 v[156:159], v156 offset:3072
	s_add_u32 s28, s28, 0x40000
	s_addc_u32 s29, s29, 0
	s_mov_b32 m0, s33
	v_lshl_add_u64 v[220:221], s[28:29], 0, v[176:177]
	ds_read_b128 v[160:163], v208 offset:32768
	ds_read_b128 v[164:167], v208 offset:33792
	ds_read_b128 v[168:171], v208 offset:34816
	ds_read_b128 v[172:175], v208 offset:35840
	ds_read_b128 v[188:191], v208 offset:36864
	ds_read_b128 v[192:195], v208 offset:37888
	ds_read_b128 v[196:199], v208 offset:38912
	ds_read_b128 v[210:213], v208 offset:39936
	global_load_lds_dwordx4 v[220:221], off
	v_lshl_add_u64 v[220:221], s[28:29], 0, v[178:179]
	s_mov_b32 m0, s34
	s_nop 0
	global_load_lds_dwordx4 v[220:221], off
	s_waitcnt vmcnt(8)
	s_waitcnt lgkmcnt(0)
	s_barrier
	s_setprio 1
	s_waitcnt lgkmcnt(0)
	v_mfma_f32_16x16x32_bf16 v[124:127], v[128:131], v[160:163], v[124:127]
	v_mfma_f32_16x16x32_bf16 v[120:123], v[136:139], v[160:163], v[120:123]
	v_mfma_f32_16x16x32_bf16 v[108:111], v[128:131], v[168:171], v[108:111]
	v_mfma_f32_16x16x32_bf16 v[104:107], v[136:139], v[168:171], v[104:107]
	v_mfma_f32_16x16x32_bf16 v[92:95], v[128:131], v[188:191], v[92:95]
	v_mfma_f32_16x16x32_bf16 v[88:91], v[136:139], v[188:191], v[88:91]
	v_mfma_f32_16x16x32_bf16 v[76:79], v[128:131], v[196:199], v[76:79]
	v_mfma_f32_16x16x32_bf16 v[72:75], v[136:139], v[196:199], v[72:75]
	v_mfma_f32_16x16x32_bf16 v[124:127], v[132:135], v[164:167], v[124:127]
	v_mfma_f32_16x16x32_bf16 v[120:123], v[140:143], v[164:167], v[120:123]
	v_mfma_f32_16x16x32_bf16 v[108:111], v[132:135], v[172:175], v[108:111]
	v_mfma_f32_16x16x32_bf16 v[104:107], v[140:143], v[172:175], v[104:107]
	v_mfma_f32_16x16x32_bf16 v[92:95], v[132:135], v[192:195], v[92:95]
	v_mfma_f32_16x16x32_bf16 v[88:91], v[140:143], v[192:195], v[88:91]
	v_mfma_f32_16x16x32_bf16 v[76:79], v[132:135], v[210:213], v[76:79]
	v_mfma_f32_16x16x32_bf16 v[72:75], v[140:143], v[210:213], v[72:75]
	s_setprio 0
	s_setprio 1
	v_mfma_f32_16x16x32_bf16 v[116:119], v[144:147], v[160:163], v[116:119]
	v_mfma_f32_16x16x32_bf16 v[112:115], v[152:155], v[160:163], v[112:115]
	v_mfma_f32_16x16x32_bf16 v[100:103], v[144:147], v[168:171], v[100:103]
	v_mfma_f32_16x16x32_bf16 v[96:99], v[152:155], v[168:171], v[96:99]
	v_mfma_f32_16x16x32_bf16 v[84:87], v[144:147], v[188:191], v[84:87]
	v_mfma_f32_16x16x32_bf16 v[80:83], v[152:155], v[188:191], v[80:83]
	v_mfma_f32_16x16x32_bf16 v[68:71], v[144:147], v[196:199], v[68:71]
	v_mfma_f32_16x16x32_bf16 v[64:67], v[152:155], v[196:199], v[64:67]
	v_mfma_f32_16x16x32_bf16 v[116:119], v[148:151], v[164:167], v[116:119]
	v_mfma_f32_16x16x32_bf16 v[112:115], v[156:159], v[164:167], v[112:115]
	v_mfma_f32_16x16x32_bf16 v[100:103], v[148:151], v[172:175], v[100:103]
	v_mfma_f32_16x16x32_bf16 v[96:99], v[156:159], v[172:175], v[96:99]
	v_mfma_f32_16x16x32_bf16 v[84:87], v[148:151], v[192:195], v[84:87]
	v_mfma_f32_16x16x32_bf16 v[80:83], v[156:159], v[192:195], v[80:83]
	v_mfma_f32_16x16x32_bf16 v[68:71], v[148:151], v[210:213], v[68:71]
	v_mfma_f32_16x16x32_bf16 v[64:67], v[156:159], v[210:213], v[64:67]
	s_setprio 0
	s_barrier
	s_add_i32 s28, s47, s30
	v_lshl_add_u64 v[200:201], v[200:201], 0, s[8:9]
	s_mov_b32 m0, s28
	ds_read_b128 v[160:163], v208 offset:49152
	ds_read_b128 v[164:167], v208 offset:50176
	ds_read_b128 v[168:171], v208 offset:51200
	ds_read_b128 v[172:175], v208 offset:52224
	ds_read_b128 v[188:191], v208 offset:53248
	ds_read_b128 v[192:195], v208 offset:54272
	ds_read_b128 v[196:199], v208 offset:55296
	ds_read_b128 v[210:213], v208 offset:56320
	global_load_lds_dwordx4 v[200:201], off
	s_add_i32 m0, s28, 0x2000
	s_add_u32 s26, s26, 0x40080
	v_lshl_add_u64 v[200:201], v[214:215], 0, s[8:9]
	s_addc_u32 s27, s27, 0
	s_add_i32 s28, s48, s30
	global_load_lds_dwordx4 v[200:201], off
	v_lshl_add_u64 v[200:201], s[26:27], 0, v[176:177]
	s_mov_b32 m0, s28
	s_nop 0
	global_load_lds_dwordx4 v[200:201], off
	v_lshl_add_u64 v[200:201], s[26:27], 0, v[178:179]
	s_add_i32 m0, s28, 0x2000
	s_nop 0
	global_load_lds_dwordx4 v[200:201], off
	v_lshl_add_u64 v[200:201], v[216:217], 0, s[8:9]
	s_mov_b32 m0, s36
	s_nop 0
	global_load_lds_dwordx4 v[200:201], off
	v_lshl_add_u64 v[200:201], v[218:219], 0, s[8:9]
	s_mov_b32 m0, s37
	s_nop 0
	global_load_lds_dwordx4 v[200:201], off
	s_waitcnt vmcnt(8)
	s_waitcnt lgkmcnt(0)
	s_barrier
	s_setprio 1
	s_waitcnt lgkmcnt(0)
	v_mfma_f32_16x16x32_bf16 v[60:63], v[128:131], v[160:163], v[60:63]
	v_mfma_f32_16x16x32_bf16 v[56:59], v[136:139], v[160:163], v[56:59]
	v_mfma_f32_16x16x32_bf16 v[44:47], v[128:131], v[168:171], v[44:47]
	v_mfma_f32_16x16x32_bf16 v[40:43], v[136:139], v[168:171], v[40:43]
	v_mfma_f32_16x16x32_bf16 v[28:31], v[128:131], v[188:191], v[28:31]
	v_mfma_f32_16x16x32_bf16 v[24:27], v[136:139], v[188:191], v[24:27]
	v_mfma_f32_16x16x32_bf16 v[12:15], v[128:131], v[196:199], v[12:15]
	v_mfma_f32_16x16x32_bf16 v[8:11], v[136:139], v[196:199], v[8:11]
	v_mfma_f32_16x16x32_bf16 v[60:63], v[132:135], v[164:167], v[60:63]
	v_mfma_f32_16x16x32_bf16 v[56:59], v[140:143], v[164:167], v[56:59]
	v_mfma_f32_16x16x32_bf16 v[44:47], v[132:135], v[172:175], v[44:47]
	v_mfma_f32_16x16x32_bf16 v[40:43], v[140:143], v[172:175], v[40:43]
	v_mfma_f32_16x16x32_bf16 v[28:31], v[132:135], v[192:195], v[28:31]
	v_mfma_f32_16x16x32_bf16 v[24:27], v[140:143], v[192:195], v[24:27]
	v_mfma_f32_16x16x32_bf16 v[12:15], v[132:135], v[210:213], v[12:15]
	v_mfma_f32_16x16x32_bf16 v[8:11], v[140:143], v[210:213], v[8:11]
	s_setprio 0
	s_setprio 1
	v_mfma_f32_16x16x32_bf16 v[52:55], v[144:147], v[160:163], v[52:55]
	v_mfma_f32_16x16x32_bf16 v[48:51], v[152:155], v[160:163], v[48:51]
	v_mfma_f32_16x16x32_bf16 v[36:39], v[144:147], v[168:171], v[36:39]
	v_mfma_f32_16x16x32_bf16 v[32:35], v[152:155], v[168:171], v[32:35]
	v_mfma_f32_16x16x32_bf16 v[20:23], v[144:147], v[188:191], v[20:23]
	v_mfma_f32_16x16x32_bf16 v[16:19], v[152:155], v[188:191], v[16:19]
	v_mfma_f32_16x16x32_bf16 v[4:7], v[144:147], v[196:199], v[4:7]
	v_mfma_f32_16x16x32_bf16 v[0:3], v[152:155], v[196:199], v[0:3]
	v_mfma_f32_16x16x32_bf16 v[52:55], v[148:151], v[164:167], v[52:55]
	v_mfma_f32_16x16x32_bf16 v[48:51], v[156:159], v[164:167], v[48:51]
	v_mfma_f32_16x16x32_bf16 v[36:39], v[148:151], v[172:175], v[36:39]
	v_mfma_f32_16x16x32_bf16 v[32:35], v[156:159], v[172:175], v[32:35]
	v_mfma_f32_16x16x32_bf16 v[20:23], v[148:151], v[192:195], v[20:23]
	v_mfma_f32_16x16x32_bf16 v[16:19], v[156:159], v[192:195], v[16:19]
	v_mfma_f32_16x16x32_bf16 v[4:7], v[148:151], v[210:213], v[4:7]
	v_mfma_f32_16x16x32_bf16 v[0:3], v[156:159], v[210:213], v[0:3]
	s_setprio 0
	s_barrier
	s_add_i32 s46, s46, 2
	s_add_u32 s24, s24, 0x100
	s_addc_u32 s25, s25, 0
	s_add_u32 s44, s44, 0x100
	s_addc_u32 s45, s45, 0
	s_cmp_gt_u32 s46, 13
	s_cbranch_scc0 .LBB0_900
	s_and_b64 vcc, exec, s[10:11]
	s_cbranch_vccz .LBB0_903
	s_barrier

.LBB0_991:
	s_ashr_i32 s21, s20, 31
	s_lshl_b64 s[22:23], s[20:21], 19
	s_add_u32 s22, s72, s22
	s_addc_u32 s23, s73, s23
	s_and_b64 s[24:25], s[4:5], exec
	s_cselect_b32 s21, s23, s31
	s_cselect_b32 s51, s22, s30
	s_ashr_i32 s19, s18, 31
	s_lshl_b64 s[24:25], s[18:19], 19
	s_add_u32 s24, s70, s24
	s_addc_u32 s25, s71, s25
	s_and_b64 s[52:53], s[4:5], exec
	s_cselect_b32 s19, s25, s29
	s_cselect_b32 s52, s24, s28
	v_lshl_add_u32 v144, s26, 8, v148
	s_add_u32 s26, s30, 0x40080
	s_addc_u32 s27, s31, 0
	v_ashrrev_i32_e32 v145, 31, v144
	s_add_u32 s53, s28, 0x100
	v_lshl_add_u64 v[146:147], v[144:145], 2, s[78:79]
	s_addc_u32 s54, s29, 0
	s_mov_b32 s55, -2
	s_waitcnt vmcnt(0)
	s_mov_b64 s[28:29], 0
	v_add_u32_e32 v161, s44, v149
	ds_read_b128 v[162:165], v161
	ds_read_b128 v[166:169], v161 offset:1024
	ds_read_b128 v[170:173], v161 offset:2048
	ds_read_b128 v[174:177], v161 offset:3072
	v_add_u32_e32 v161, s45, v149
	ds_read_b128 v[178:181], v161
	ds_read_b128 v[182:185], v161 offset:1024
	ds_read_b128 v[186:189], v161 offset:2048
	ds_read_b128 v[190:193], v161 offset:3072
	s_add_u32 s30, s26, 0xfffc0080
	s_addc_u32 s31, s27, -1
	s_and_b64 s[28:29], s[28:29], exec
	s_cselect_b32 s31, s21, s31
	s_cselect_b32 s30, s51, s30
	s_cselect_b32 s29, s19, s54
	s_cselect_b32 s28, s52, s53
	v_lshl_add_u64 v[228:229], s[26:27], 0, v[136:137]
	s_add_i32 m0, s35, 0xc000
	ds_read_b128 v[194:197], v151
	ds_read_b128 v[198:201], v151 offset:1024
	ds_read_b128 v[204:207], v151 offset:2048
	ds_read_b128 v[208:211], v151 offset:3072
	ds_read_b128 v[212:215], v151 offset:4096
	ds_read_b128 v[216:219], v151 offset:5120
	ds_read_b128 v[220:223], v151 offset:6144
	ds_read_b128 v[224:227], v151 offset:7168
	global_load_lds_dwordx4 v[228:229], off
	v_lshl_add_u64 v[228:229], s[26:27], 0, v[138:139]
	s_add_i32 m0, s35, 0xe000
	s_nop 0
	global_load_lds_dwordx4 v[228:229], off
	s_waitcnt vmcnt(8)
	s_waitcnt lgkmcnt(0)
	s_barrier
	s_setprio 1
	s_waitcnt lgkmcnt(0)
	v_mfma_f32_16x16x32_bf16 v[124:127], v[162:165], v[194:197], 0
	v_mfma_f32_16x16x32_bf16 v[120:123], v[170:173], v[194:197], 0
	v_mfma_f32_16x16x32_bf16 v[108:111], v[162:165], v[204:207], 0
	v_mfma_f32_16x16x32_bf16 v[104:107], v[170:173], v[204:207], 0
	v_mfma_f32_16x16x32_bf16 v[92:95], v[162:165], v[212:215], 0
	v_mfma_f32_16x16x32_bf16 v[88:91], v[170:173], v[212:215], 0
	v_mfma_f32_16x16x32_bf16 v[76:79], v[162:165], v[220:223], 0
	v_mfma_f32_16x16x32_bf16 v[72:75], v[170:173], v[220:223], 0
	v_mfma_f32_16x16x32_bf16 v[124:127], v[166:169], v[198:201], v[124:127]
	v_mfma_f32_16x16x32_bf16 v[120:123], v[174:177], v[198:201], v[120:123]
	v_mfma_f32_16x16x32_bf16 v[108:111], v[166:169], v[208:211], v[108:111]
	v_mfma_f32_16x16x32_bf16 v[104:107], v[174:177], v[208:211], v[104:107]
	v_mfma_f32_16x16x32_bf16 v[92:95], v[166:169], v[216:219], v[92:95]
	v_mfma_f32_16x16x32_bf16 v[88:91], v[174:177], v[216:219], v[88:91]
	v_mfma_f32_16x16x32_bf16 v[76:79], v[166:169], v[224:227], v[76:79]
	v_mfma_f32_16x16x32_bf16 v[72:75], v[174:177], v[224:227], v[72:75]
	s_setprio 0
	s_setprio 1
	v_mfma_f32_16x16x32_bf16 v[116:119], v[178:181], v[194:197], 0
	v_mfma_f32_16x16x32_bf16 v[112:115], v[186:189], v[194:197], 0
	v_mfma_f32_16x16x32_bf16 v[100:103], v[178:181], v[204:207], 0
	v_mfma_f32_16x16x32_bf16 v[96:99], v[186:189], v[204:207], 0
	v_mfma_f32_16x16x32_bf16 v[84:87], v[178:181], v[212:215], 0
	v_mfma_f32_16x16x32_bf16 v[80:83], v[186:189], v[212:215], 0
	v_mfma_f32_16x16x32_bf16 v[68:71], v[178:181], v[220:223], 0
	v_mfma_f32_16x16x32_bf16 v[64:67], v[186:189], v[220:223], 0
	v_mfma_f32_16x16x32_bf16 v[116:119], v[182:185], v[198:201], v[116:119]
	v_mfma_f32_16x16x32_bf16 v[112:115], v[190:193], v[198:201], v[112:115]
	v_mfma_f32_16x16x32_bf16 v[100:103], v[182:185], v[208:211], v[100:103]
	v_mfma_f32_16x16x32_bf16 v[96:99], v[190:193], v[208:211], v[96:99]
	v_mfma_f32_16x16x32_bf16 v[84:87], v[182:185], v[216:219], v[84:87]
	v_mfma_f32_16x16x32_bf16 v[80:83], v[190:193], v[216:219], v[80:83]
	v_mfma_f32_16x16x32_bf16 v[68:71], v[182:185], v[224:227], v[68:71]
	v_mfma_f32_16x16x32_bf16 v[64:67], v[190:193], v[224:227], v[64:67]
	s_setprio 0
	s_barrier
	s_add_i32 s56, s44, s34
	v_lshl_add_u64 v[228:229], s[28:29], 0, v[130:131]
	s_mov_b32 m0, s56
	ds_read_b128 v[194:197], v151 offset:16384
	ds_read_b128 v[198:201], v151 offset:17408
	ds_read_b128 v[204:207], v151 offset:18432
	ds_read_b128 v[208:211], v151 offset:19456
	ds_read_b128 v[212:215], v151 offset:20480
	ds_read_b128 v[216:219], v151 offset:21504
	ds_read_b128 v[220:223], v151 offset:22528
	ds_read_b128 v[224:227], v151 offset:23552
	global_load_lds_dwordx4 v[228:229], off
	s_add_i32 m0, s56, 0x2000
	s_add_u32 s56, s28, 0x40000
	v_lshl_add_u64 v[230:231], s[28:29], 0, v[134:135]
	s_addc_u32 s57, s29, 0
	s_add_i32 s58, s45, s34
	global_load_lds_dwordx4 v[230:231], off
	v_lshl_add_u64 v[232:233], s[56:57], 0, v[130:131]
	s_mov_b32 m0, s58
	v_lshl_add_u64 v[234:235], s[30:31], 0, v[132:133]
	global_load_lds_dwordx4 v[232:233], off
	v_lshl_add_u64 v[232:233], s[56:57], 0, v[134:135]
	s_add_i32 m0, s58, 0x2000
	s_nop 0
	global_load_lds_dwordx4 v[232:233], off
	v_lshl_add_u64 v[232:233], s[30:31], 0, v[128:129]
	s_mov_b32 m0, s35
	s_nop 0
	global_load_lds_dwordx4 v[232:233], off
	s_mov_b32 m0, s36
	s_nop 0
	global_load_lds_dwordx4 v[234:235], off
	s_waitcnt vmcnt(8)
	s_waitcnt lgkmcnt(0)
	s_barrier
	s_setprio 1
	s_waitcnt lgkmcnt(0)
	v_mfma_f32_16x16x32_bf16 v[60:63], v[162:165], v[194:197], 0
	v_mfma_f32_16x16x32_bf16 v[56:59], v[170:173], v[194:197], 0
	v_mfma_f32_16x16x32_bf16 v[44:47], v[162:165], v[204:207], 0
	v_mfma_f32_16x16x32_bf16 v[40:43], v[170:173], v[204:207], 0
	v_mfma_f32_16x16x32_bf16 v[28:31], v[162:165], v[212:215], 0
	v_mfma_f32_16x16x32_bf16 v[24:27], v[170:173], v[212:215], 0
	v_mfma_f32_16x16x32_bf16 v[12:15], v[162:165], v[220:223], 0
	v_mfma_f32_16x16x32_bf16 v[8:11], v[170:173], v[220:223], 0
	v_mfma_f32_16x16x32_bf16 v[60:63], v[166:169], v[198:201], v[60:63]
	v_mfma_f32_16x16x32_bf16 v[56:59], v[174:177], v[198:201], v[56:59]
	v_mfma_f32_16x16x32_bf16 v[44:47], v[166:169], v[208:211], v[44:47]
	v_mfma_f32_16x16x32_bf16 v[40:43], v[174:177], v[208:211], v[40:43]
	v_mfma_f32_16x16x32_bf16 v[28:31], v[166:169], v[216:219], v[28:31]
	v_mfma_f32_16x16x32_bf16 v[24:27], v[174:177], v[216:219], v[24:27]
	v_mfma_f32_16x16x32_bf16 v[12:15], v[166:169], v[224:227], v[12:15]
	v_mfma_f32_16x16x32_bf16 v[8:11], v[174:177], v[224:227], v[8:11]
	s_setprio 0
	s_setprio 1
	v_mfma_f32_16x16x32_bf16 v[52:55], v[178:181], v[194:197], 0
	v_mfma_f32_16x16x32_bf16 v[48:51], v[186:189], v[194:197], 0
	v_mfma_f32_16x16x32_bf16 v[36:39], v[178:181], v[204:207], 0
	v_mfma_f32_16x16x32_bf16 v[32:35], v[186:189], v[204:207], 0
	v_mfma_f32_16x16x32_bf16 v[20:23], v[178:181], v[212:215], 0
	v_mfma_f32_16x16x32_bf16 v[16:19], v[186:189], v[212:215], 0
	v_mfma_f32_16x16x32_bf16 v[4:7], v[178:181], v[220:223], 0
	v_mfma_f32_16x16x32_bf16 v[0:3], v[186:189], v[220:223], 0
	v_mfma_f32_16x16x32_bf16 v[52:55], v[182:185], v[198:201], v[52:55]
	v_mfma_f32_16x16x32_bf16 v[48:51], v[190:193], v[198:201], v[48:51]
	v_mfma_f32_16x16x32_bf16 v[36:39], v[182:185], v[208:211], v[36:39]
	v_mfma_f32_16x16x32_bf16 v[32:35], v[190:193], v[208:211], v[32:35]
	v_mfma_f32_16x16x32_bf16 v[20:23], v[182:185], v[216:219], v[20:23]
	v_mfma_f32_16x16x32_bf16 v[16:19], v[190:193], v[216:219], v[16:19]
	v_mfma_f32_16x16x32_bf16 v[4:7], v[182:185], v[224:227], v[4:7]
	v_mfma_f32_16x16x32_bf16 v[0:3], v[190:193], v[224:227], v[0:3]
	s_setprio 0
	s_barrier
	s_branch .Lpeel_mid_b992

.Lpeel_mid_b992:
	s_add_i32 s56, 0, 0x18000
	v_add_u32_e32 v161, s56, v149
	s_add_i32 s57, 0, 0x1c000
	ds_read_b128 v[162:165], v161
	ds_read_b128 v[166:169], v161 offset:1024
	ds_read_b128 v[170:173], v161 offset:2048
	ds_read_b128 v[174:177], v161 offset:3072
	v_add_u32_e32 v161, s57, v149
	ds_read_b128 v[178:181], v161
	ds_read_b128 v[182:185], v161 offset:1024
	ds_read_b128 v[186:189], v161 offset:2048
	ds_read_b128 v[190:193], v161 offset:3072
	s_add_u32 s30, s30, 0x40000
	s_addc_u32 s31, s31, 0
	s_mov_b32 m0, s37
	v_lshl_add_u64 v[236:237], s[30:31], 0, v[128:129]
	ds_read_b128 v[194:197], v151 offset:32768
	ds_read_b128 v[198:201], v151 offset:33792
	ds_read_b128 v[204:207], v151 offset:34816
	ds_read_b128 v[208:211], v151 offset:35840
	ds_read_b128 v[212:215], v151 offset:36864
	ds_read_b128 v[216:219], v151 offset:37888
	ds_read_b128 v[220:223], v151 offset:38912
	ds_read_b128 v[224:227], v151 offset:39936
	global_load_lds_dwordx4 v[236:237], off
	v_lshl_add_u64 v[236:237], s[30:31], 0, v[132:133]
	s_mov_b32 m0, s38
	s_nop 0
	global_load_lds_dwordx4 v[236:237], off
	s_waitcnt vmcnt(8)
	s_waitcnt lgkmcnt(0)
	s_barrier
	s_setprio 1
	s_waitcnt lgkmcnt(0)
	v_mfma_f32_16x16x32_bf16 v[124:127], v[162:165], v[194:197], v[124:127]
	v_mfma_f32_16x16x32_bf16 v[120:123], v[170:173], v[194:197], v[120:123]
	v_mfma_f32_16x16x32_bf16 v[108:111], v[162:165], v[204:207], v[108:111]
	v_mfma_f32_16x16x32_bf16 v[104:107], v[170:173], v[204:207], v[104:107]
	v_mfma_f32_16x16x32_bf16 v[92:95], v[162:165], v[212:215], v[92:95]
	v_mfma_f32_16x16x32_bf16 v[88:91], v[170:173], v[212:215], v[88:91]
	v_mfma_f32_16x16x32_bf16 v[76:79], v[162:165], v[220:223], v[76:79]
	v_mfma_f32_16x16x32_bf16 v[72:75], v[170:173], v[220:223], v[72:75]
	v_mfma_f32_16x16x32_bf16 v[124:127], v[166:169], v[198:201], v[124:127]
	v_mfma_f32_16x16x32_bf16 v[120:123], v[174:177], v[198:201], v[120:123]
	v_mfma_f32_16x16x32_bf16 v[108:111], v[166:169], v[208:211], v[108:111]
	v_mfma_f32_16x16x32_bf16 v[104:107], v[174:177], v[208:211], v[104:107]
	v_mfma_f32_16x16x32_bf16 v[92:95], v[166:169], v[216:219], v[92:95]
	v_mfma_f32_16x16x32_bf16 v[88:91], v[174:177], v[216:219], v[88:91]
	v_mfma_f32_16x16x32_bf16 v[76:79], v[166:169], v[224:227], v[76:79]
	v_mfma_f32_16x16x32_bf16 v[72:75], v[174:177], v[224:227], v[72:75]
	s_setprio 0
	s_setprio 1
	v_mfma_f32_16x16x32_bf16 v[116:119], v[178:181], v[194:197], v[116:119]
	v_mfma_f32_16x16x32_bf16 v[112:115], v[186:189], v[194:197], v[112:115]
	v_mfma_f32_16x16x32_bf16 v[100:103], v[178:181], v[204:207], v[100:103]
	v_mfma_f32_16x16x32_bf16 v[96:99], v[186:189], v[204:207], v[96:99]
	v_mfma_f32_16x16x32_bf16 v[84:87], v[178:181], v[212:215], v[84:87]
	v_mfma_f32_16x16x32_bf16 v[80:83], v[186:189], v[212:215], v[80:83]
	v_mfma_f32_16x16x32_bf16 v[68:71], v[178:181], v[220:223], v[68:71]
	v_mfma_f32_16x16x32_bf16 v[64:67], v[186:189], v[220:223], v[64:67]
	v_mfma_f32_16x16x32_bf16 v[116:119], v[182:185], v[198:201], v[116:119]
	v_mfma_f32_16x16x32_bf16 v[112:115], v[190:193], v[198:201], v[112:115]
	v_mfma_f32_16x16x32_bf16 v[100:103], v[182:185], v[208:211], v[100:103]
	v_mfma_f32_16x16x32_bf16 v[96:99], v[190:193], v[208:211], v[96:99]
	v_mfma_f32_16x16x32_bf16 v[84:87], v[182:185], v[216:219], v[84:87]
	v_mfma_f32_16x16x32_bf16 v[80:83], v[190:193], v[216:219], v[80:83]
	v_mfma_f32_16x16x32_bf16 v[68:71], v[182:185], v[224:227], v[68:71]
	v_mfma_f32_16x16x32_bf16 v[64:67], v[190:193], v[224:227], v[64:67]
	s_setprio 0
	s_barrier
	s_add_i32 s30, s56, s34
	v_lshl_add_u64 v[228:229], v[228:229], 0, s[6:7]
	s_mov_b32 m0, s30
	ds_read_b128 v[194:197], v151 offset:49152
	ds_read_b128 v[198:201], v151 offset:50176
	ds_read_b128 v[204:207], v151 offset:51200
	ds_read_b128 v[208:211], v151 offset:52224
	ds_read_b128 v[212:215], v151 offset:53248
	ds_read_b128 v[216:219], v151 offset:54272
	ds_read_b128 v[220:223], v151 offset:55296
	ds_read_b128 v[224:227], v151 offset:56320
	global_load_lds_dwordx4 v[228:229], off
	s_add_i32 m0, s30, 0x2000
	s_add_u32 s28, s28, 0x40080
	v_lshl_add_u64 v[228:229], v[230:231], 0, s[6:7]
	s_addc_u32 s29, s29, 0
	s_add_i32 s30, s57, s34
	global_load_lds_dwordx4 v[228:229], off
	v_lshl_add_u64 v[228:229], s[28:29], 0, v[130:131]
	s_mov_b32 m0, s30
	s_nop 0
	global_load_lds_dwordx4 v[228:229], off
	v_lshl_add_u64 v[228:229], s[28:29], 0, v[134:135]
	s_add_i32 m0, s30, 0x2000
	s_nop 0
	global_load_lds_dwordx4 v[228:229], off
	v_lshl_add_u64 v[228:229], v[232:233], 0, s[6:7]
	s_mov_b32 m0, s40
	s_nop 0
	global_load_lds_dwordx4 v[228:229], off
	v_lshl_add_u64 v[228:229], v[234:235], 0, s[6:7]
	s_mov_b32 m0, s41
	s_nop 0
	global_load_lds_dwordx4 v[228:229], off
	s_waitcnt vmcnt(8)
	s_waitcnt lgkmcnt(0)
	s_barrier
	s_setprio 1
	s_waitcnt lgkmcnt(0)
	v_mfma_f32_16x16x32_bf16 v[60:63], v[162:165], v[194:197], v[60:63]
	v_mfma_f32_16x16x32_bf16 v[56:59], v[170:173], v[194:197], v[56:59]
	v_mfma_f32_16x16x32_bf16 v[44:47], v[162:165], v[204:207], v[44:47]
	v_mfma_f32_16x16x32_bf16 v[40:43], v[170:173], v[204:207], v[40:43]
	v_mfma_f32_16x16x32_bf16 v[28:31], v[162:165], v[212:215], v[28:31]
	v_mfma_f32_16x16x32_bf16 v[24:27], v[170:173], v[212:215], v[24:27]
	v_mfma_f32_16x16x32_bf16 v[12:15], v[162:165], v[220:223], v[12:15]
	v_mfma_f32_16x16x32_bf16 v[8:11], v[170:173], v[220:223], v[8:11]
	v_mfma_f32_16x16x32_bf16 v[60:63], v[166:169], v[198:201], v[60:63]
	v_mfma_f32_16x16x32_bf16 v[56:59], v[174:177], v[198:201], v[56:59]
	v_mfma_f32_16x16x32_bf16 v[44:47], v[166:169], v[208:211], v[44:47]
	v_mfma_f32_16x16x32_bf16 v[40:43], v[174:177], v[208:211], v[40:43]
	v_mfma_f32_16x16x32_bf16 v[28:31], v[166:169], v[216:219], v[28:31]
	v_mfma_f32_16x16x32_bf16 v[24:27], v[174:177], v[216:219], v[24:27]
	v_mfma_f32_16x16x32_bf16 v[12:15], v[166:169], v[224:227], v[12:15]
	v_mfma_f32_16x16x32_bf16 v[8:11], v[174:177], v[224:227], v[8:11]
	s_setprio 0
	s_setprio 1
	v_mfma_f32_16x16x32_bf16 v[52:55], v[178:181], v[194:197], v[52:55]
	v_mfma_f32_16x16x32_bf16 v[48:51], v[186:189], v[194:197], v[48:51]
	v_mfma_f32_16x16x32_bf16 v[36:39], v[178:181], v[204:207], v[36:39]
	v_mfma_f32_16x16x32_bf16 v[32:35], v[186:189], v[204:207], v[32:35]
	v_mfma_f32_16x16x32_bf16 v[20:23], v[178:181], v[212:215], v[20:23]
	v_mfma_f32_16x16x32_bf16 v[16:19], v[186:189], v[212:215], v[16:19]
	v_mfma_f32_16x16x32_bf16 v[4:7], v[178:181], v[220:223], v[4:7]
	v_mfma_f32_16x16x32_bf16 v[0:3], v[186:189], v[220:223], v[0:3]
	v_mfma_f32_16x16x32_bf16 v[52:55], v[182:185], v[198:201], v[52:55]
	v_mfma_f32_16x16x32_bf16 v[48:51], v[190:193], v[198:201], v[48:51]
	v_mfma_f32_16x16x32_bf16 v[36:39], v[182:185], v[208:211], v[36:39]
	v_mfma_f32_16x16x32_bf16 v[32:35], v[190:193], v[208:211], v[32:35]
	v_mfma_f32_16x16x32_bf16 v[20:23], v[182:185], v[216:219], v[20:23]
	v_mfma_f32_16x16x32_bf16 v[16:19], v[190:193], v[216:219], v[16:19]
	v_mfma_f32_16x16x32_bf16 v[4:7], v[182:185], v[224:227], v[4:7]
	v_mfma_f32_16x16x32_bf16 v[0:3], v[190:193], v[224:227], v[0:3]
	s_setprio 0
	s_barrier
	s_add_i32 s55, s55, 2
	s_add_u32 s26, s26, 0x100
	s_addc_u32 s27, s27, 0
	s_add_u32 s53, s53, 0x100
	s_addc_u32 s54, s54, 0
	s_cmp_gt_u32 s55, 13
	s_cbranch_scc1 .LBB0_995

.LBB0_1069:
	s_ashr_i32 s11, s10, 31
	s_lshl_b64 s[12:13], s[10:11], 21
	s_add_u32 s12, s74, s12
	s_addc_u32 s13, s75, s13
	s_and_b64 s[14:15], s[0:1], exec
	s_cselect_b32 s11, s13, s19
	s_cselect_b32 s37, s12, s18
	s_ashr_i32 s9, s8, 31
	s_lshl_b64 s[14:15], s[8:9], 21
	s_add_u32 s14, s46, s14
	s_addc_u32 s15, s47, s15
	s_and_b64 s[22:23], s[0:1], exec
	s_cselect_b32 s9, s15, s21
	s_cselect_b32 s38, s14, s20
	s_add_u32 s18, s18, 0x100080
	s_addc_u32 s19, s19, 0
	s_add_u32 s39, s20, 0x100
	s_addc_u32 s40, s21, 0
	s_mov_b32 s41, -2
	s_waitcnt vmcnt(0)
	ds_read_b128 v[140:143], v193
	ds_read_b128 v[144:147], v193 offset:1024
	ds_read_b128 v[148:151], v193 offset:2048
	ds_read_b128 v[152:155], v193 offset:3072
	ds_read_b128 v[156:159], v194
	ds_read_b128 v[160:163], v194 offset:1024
	ds_read_b128 v[164:167], v194 offset:2048
	ds_read_b128 v[168:171], v194 offset:3072
	s_add_u32 s20, s18, 0xfff00080
	s_addc_u32 s21, s19, -1
	s_cmp_eq_u32 s41, 60
	s_cselect_b32 s23, s11, s21
	s_cselect_b32 s22, s37, s20
	s_cselect_b32 s21, s9, s40
	s_cselect_b32 s20, s38, s39
	v_lshl_add_u64 v[188:189], s[18:19], 0, v[132:133]
	s_add_i32 m0, s17, 0xc000
	ds_read_b128 v[172:175], v195
	ds_read_b128 v[176:179], v195 offset:1024
	ds_read_b128 v[180:183], v195 offset:2048
	ds_read_b128 v[184:187], v195 offset:3072
	ds_read_b128 v[196:199], v195 offset:4096
	ds_read_b128 v[200:203], v195 offset:5120
	ds_read_b128 v[204:207], v195 offset:6144
	ds_read_b128 v[208:211], v195 offset:7168
	global_load_lds_dwordx4 v[188:189], off
	v_lshl_add_u64 v[188:189], s[18:19], 0, v[134:135]
	s_add_i32 m0, s17, 0xe000
	s_nop 0
	global_load_lds_dwordx4 v[188:189], off
	s_waitcnt vmcnt(8)
	s_waitcnt lgkmcnt(0)
	s_barrier
	s_setprio 1
	s_waitcnt lgkmcnt(0)
	v_mfma_f32_16x16x32_bf16 v[124:127], v[140:143], v[172:175], 0
	v_mfma_f32_16x16x32_bf16 v[120:123], v[148:151], v[172:175], 0
	v_mfma_f32_16x16x32_bf16 v[112:115], v[140:143], v[180:183], 0
	v_mfma_f32_16x16x32_bf16 v[104:107], v[148:151], v[180:183], 0
	v_mfma_f32_16x16x32_bf16 v[96:99], v[140:143], v[196:199], 0
	v_mfma_f32_16x16x32_bf16 v[88:91], v[148:151], v[196:199], 0
	v_mfma_f32_16x16x32_bf16 v[80:83], v[140:143], v[204:207], 0
	v_mfma_f32_16x16x32_bf16 v[72:75], v[148:151], v[204:207], 0
	v_mfma_f32_16x16x32_bf16 v[124:127], v[144:147], v[176:179], v[124:127]
	v_mfma_f32_16x16x32_bf16 v[120:123], v[152:155], v[176:179], v[120:123]
	v_mfma_f32_16x16x32_bf16 v[112:115], v[144:147], v[184:187], v[112:115]
	v_mfma_f32_16x16x32_bf16 v[104:107], v[152:155], v[184:187], v[104:107]
	v_mfma_f32_16x16x32_bf16 v[96:99], v[144:147], v[200:203], v[96:99]
	v_mfma_f32_16x16x32_bf16 v[88:91], v[152:155], v[200:203], v[88:91]
	v_mfma_f32_16x16x32_bf16 v[80:83], v[144:147], v[208:211], v[80:83]
	v_mfma_f32_16x16x32_bf16 v[72:75], v[152:155], v[208:211], v[72:75]
	s_setprio 0
	s_setprio 1
	v_mfma_f32_16x16x32_bf16 v[116:119], v[156:159], v[172:175], 0
	v_mfma_f32_16x16x32_bf16 v[108:111], v[164:167], v[172:175], 0
	v_mfma_f32_16x16x32_bf16 v[100:103], v[156:159], v[180:183], 0
	v_mfma_f32_16x16x32_bf16 v[92:95], v[164:167], v[180:183], 0
	v_mfma_f32_16x16x32_bf16 v[84:87], v[156:159], v[196:199], 0
	v_mfma_f32_16x16x32_bf16 v[76:79], v[164:167], v[196:199], 0
	v_mfma_f32_16x16x32_bf16 v[68:71], v[156:159], v[204:207], 0
	v_mfma_f32_16x16x32_bf16 v[64:67], v[164:167], v[204:207], 0
	v_mfma_f32_16x16x32_bf16 v[116:119], v[160:163], v[176:179], v[116:119]
	v_mfma_f32_16x16x32_bf16 v[108:111], v[168:171], v[176:179], v[108:111]
	v_mfma_f32_16x16x32_bf16 v[100:103], v[160:163], v[184:187], v[100:103]
	v_mfma_f32_16x16x32_bf16 v[92:95], v[168:171], v[184:187], v[92:95]
	v_mfma_f32_16x16x32_bf16 v[84:87], v[160:163], v[200:203], v[84:87]
	v_mfma_f32_16x16x32_bf16 v[76:79], v[168:171], v[200:203], v[76:79]
	v_mfma_f32_16x16x32_bf16 v[68:71], v[160:163], v[208:211], v[68:71]
	v_mfma_f32_16x16x32_bf16 v[64:67], v[168:171], v[208:211], v[64:67]
	s_setprio 0
	s_barrier
	s_add_i32 s42, s34, s25
	v_lshl_add_u64 v[188:189], s[20:21], 0, v[128:129]
	s_mov_b32 m0, s42
	ds_read_b128 v[172:175], v195 offset:16384
	ds_read_b128 v[176:179], v195 offset:17408
	ds_read_b128 v[180:183], v195 offset:18432
	ds_read_b128 v[184:187], v195 offset:19456
	ds_read_b128 v[196:199], v195 offset:20480
	ds_read_b128 v[200:203], v195 offset:21504
	ds_read_b128 v[204:207], v195 offset:22528
	ds_read_b128 v[208:211], v195 offset:23552
	global_load_lds_dwordx4 v[188:189], off
	s_add_i32 m0, s42, 0x2000
	s_add_u32 s42, s20, 0x100000
	v_lshl_add_u64 v[212:213], s[20:21], 0, v[130:131]
	s_addc_u32 s43, s21, 0
	s_add_i32 s44, s35, s25
	global_load_lds_dwordx4 v[212:213], off
	v_lshl_add_u64 v[214:215], s[42:43], 0, v[128:129]
	s_mov_b32 m0, s44
	v_lshl_add_u64 v[216:217], s[22:23], 0, v[130:131]
	global_load_lds_dwordx4 v[214:215], off
	v_lshl_add_u64 v[214:215], s[42:43], 0, v[130:131]
	s_add_i32 m0, s44, 0x2000
	s_nop 0
	global_load_lds_dwordx4 v[214:215], off
	v_lshl_add_u64 v[214:215], s[22:23], 0, v[128:129]
	s_mov_b32 m0, s17
	s_nop 0
	global_load_lds_dwordx4 v[214:215], off
	s_mov_b32 m0, s26
	s_nop 0
	global_load_lds_dwordx4 v[216:217], off
	s_waitcnt vmcnt(8)
	s_waitcnt lgkmcnt(0)
	s_barrier
	s_setprio 1
	s_waitcnt lgkmcnt(0)
	v_mfma_f32_16x16x32_bf16 v[60:63], v[140:143], v[172:175], 0
	v_mfma_f32_16x16x32_bf16 v[56:59], v[148:151], v[172:175], 0
	v_mfma_f32_16x16x32_bf16 v[48:51], v[140:143], v[180:183], 0
	v_mfma_f32_16x16x32_bf16 v[40:43], v[148:151], v[180:183], 0
	v_mfma_f32_16x16x32_bf16 v[32:35], v[140:143], v[196:199], 0
	v_mfma_f32_16x16x32_bf16 v[24:27], v[148:151], v[196:199], 0
	v_mfma_f32_16x16x32_bf16 v[16:19], v[140:143], v[204:207], 0
	v_mfma_f32_16x16x32_bf16 v[8:11], v[148:151], v[204:207], 0
	v_mfma_f32_16x16x32_bf16 v[60:63], v[144:147], v[176:179], v[60:63]
	v_mfma_f32_16x16x32_bf16 v[56:59], v[152:155], v[176:179], v[56:59]
	v_mfma_f32_16x16x32_bf16 v[48:51], v[144:147], v[184:187], v[48:51]
	v_mfma_f32_16x16x32_bf16 v[40:43], v[152:155], v[184:187], v[40:43]
	v_mfma_f32_16x16x32_bf16 v[32:35], v[144:147], v[200:203], v[32:35]
	v_mfma_f32_16x16x32_bf16 v[24:27], v[152:155], v[200:203], v[24:27]
	v_mfma_f32_16x16x32_bf16 v[16:19], v[144:147], v[208:211], v[16:19]
	v_mfma_f32_16x16x32_bf16 v[8:11], v[152:155], v[208:211], v[8:11]
	s_setprio 0
	s_setprio 1
	v_mfma_f32_16x16x32_bf16 v[52:55], v[156:159], v[172:175], 0
	v_mfma_f32_16x16x32_bf16 v[44:47], v[164:167], v[172:175], 0
	v_mfma_f32_16x16x32_bf16 v[36:39], v[156:159], v[180:183], 0
	v_mfma_f32_16x16x32_bf16 v[28:31], v[164:167], v[180:183], 0
	v_mfma_f32_16x16x32_bf16 v[20:23], v[156:159], v[196:199], 0
	v_mfma_f32_16x16x32_bf16 v[12:15], v[164:167], v[196:199], 0
	v_mfma_f32_16x16x32_bf16 v[4:7], v[156:159], v[204:207], 0
	v_mfma_f32_16x16x32_bf16 v[0:3], v[164:167], v[204:207], 0
	v_mfma_f32_16x16x32_bf16 v[52:55], v[160:163], v[176:179], v[52:55]
	v_mfma_f32_16x16x32_bf16 v[44:47], v[168:171], v[176:179], v[44:47]
	v_mfma_f32_16x16x32_bf16 v[36:39], v[160:163], v[184:187], v[36:39]
	v_mfma_f32_16x16x32_bf16 v[28:31], v[168:171], v[184:187], v[28:31]
	v_mfma_f32_16x16x32_bf16 v[20:23], v[160:163], v[200:203], v[20:23]
	v_mfma_f32_16x16x32_bf16 v[12:15], v[168:171], v[200:203], v[12:15]
	v_mfma_f32_16x16x32_bf16 v[4:7], v[160:163], v[208:211], v[4:7]
	v_mfma_f32_16x16x32_bf16 v[0:3], v[168:171], v[208:211], v[0:3]
	s_setprio 0
	s_barrier
	s_branch .Lpeel_mid_b1070

.Lpeel_mid_b1070:
	s_add_i32 s42, 0, 0x18000
	s_add_i32 s43, 0, 0x1c000
	v_add_u32_e32 v152, s42, v191
	v_add_u32_e32 v168, s43, v191
	ds_read_b128 v[140:143], v152
	ds_read_b128 v[144:147], v152 offset:1024
	ds_read_b128 v[148:151], v152 offset:2048
	ds_read_b128 v[152:155], v152 offset:3072
	ds_read_b128 v[156:159], v168
	ds_read_b128 v[160:163], v168 offset:1024
	ds_read_b128 v[164:167], v168 offset:2048
	ds_read_b128 v[168:171], v168 offset:3072
	s_add_u32 s22, s22, 0x100000
	s_addc_u32 s23, s23, 0
	s_mov_b32 m0, s27
	v_lshl_add_u64 v[218:219], s[22:23], 0, v[128:129]
	ds_read_b128 v[172:175], v195 offset:32768
	ds_read_b128 v[176:179], v195 offset:33792
	ds_read_b128 v[180:183], v195 offset:34816
	ds_read_b128 v[184:187], v195 offset:35840
	ds_read_b128 v[196:199], v195 offset:36864
	ds_read_b128 v[200:203], v195 offset:37888
	ds_read_b128 v[204:207], v195 offset:38912
	ds_read_b128 v[208:211], v195 offset:39936
	global_load_lds_dwordx4 v[218:219], off
	v_lshl_add_u64 v[218:219], s[22:23], 0, v[130:131]
	s_mov_b32 m0, s28
	s_nop 0
	global_load_lds_dwordx4 v[218:219], off
	s_waitcnt vmcnt(8)
	s_waitcnt lgkmcnt(0)
	s_barrier
	s_setprio 1
	s_waitcnt lgkmcnt(0)
	v_mfma_f32_16x16x32_bf16 v[124:127], v[140:143], v[172:175], v[124:127]
	v_mfma_f32_16x16x32_bf16 v[120:123], v[148:151], v[172:175], v[120:123]
	v_mfma_f32_16x16x32_bf16 v[112:115], v[140:143], v[180:183], v[112:115]
	v_mfma_f32_16x16x32_bf16 v[104:107], v[148:151], v[180:183], v[104:107]
	v_mfma_f32_16x16x32_bf16 v[96:99], v[140:143], v[196:199], v[96:99]
	v_mfma_f32_16x16x32_bf16 v[88:91], v[148:151], v[196:199], v[88:91]
	v_mfma_f32_16x16x32_bf16 v[80:83], v[140:143], v[204:207], v[80:83]
	v_mfma_f32_16x16x32_bf16 v[72:75], v[148:151], v[204:207], v[72:75]
	v_mfma_f32_16x16x32_bf16 v[124:127], v[144:147], v[176:179], v[124:127]
	v_mfma_f32_16x16x32_bf16 v[120:123], v[152:155], v[176:179], v[120:123]
	v_mfma_f32_16x16x32_bf16 v[112:115], v[144:147], v[184:187], v[112:115]
	v_mfma_f32_16x16x32_bf16 v[104:107], v[152:155], v[184:187], v[104:107]
	v_mfma_f32_16x16x32_bf16 v[96:99], v[144:147], v[200:203], v[96:99]
	v_mfma_f32_16x16x32_bf16 v[88:91], v[152:155], v[200:203], v[88:91]
	v_mfma_f32_16x16x32_bf16 v[80:83], v[144:147], v[208:211], v[80:83]
	v_mfma_f32_16x16x32_bf16 v[72:75], v[152:155], v[208:211], v[72:75]
	s_setprio 0
	s_setprio 1
	v_mfma_f32_16x16x32_bf16 v[116:119], v[156:159], v[172:175], v[116:119]
	v_mfma_f32_16x16x32_bf16 v[108:111], v[164:167], v[172:175], v[108:111]
	v_mfma_f32_16x16x32_bf16 v[100:103], v[156:159], v[180:183], v[100:103]
	v_mfma_f32_16x16x32_bf16 v[92:95], v[164:167], v[180:183], v[92:95]
	v_mfma_f32_16x16x32_bf16 v[84:87], v[156:159], v[196:199], v[84:87]
	v_mfma_f32_16x16x32_bf16 v[76:79], v[164:167], v[196:199], v[76:79]
	v_mfma_f32_16x16x32_bf16 v[68:71], v[156:159], v[204:207], v[68:71]
	v_mfma_f32_16x16x32_bf16 v[64:67], v[164:167], v[204:207], v[64:67]
	v_mfma_f32_16x16x32_bf16 v[116:119], v[160:163], v[176:179], v[116:119]
	v_mfma_f32_16x16x32_bf16 v[108:111], v[168:171], v[176:179], v[108:111]
	v_mfma_f32_16x16x32_bf16 v[100:103], v[160:163], v[184:187], v[100:103]
	v_mfma_f32_16x16x32_bf16 v[92:95], v[168:171], v[184:187], v[92:95]
	v_mfma_f32_16x16x32_bf16 v[84:87], v[160:163], v[200:203], v[84:87]
	v_mfma_f32_16x16x32_bf16 v[76:79], v[168:171], v[200:203], v[76:79]
	v_mfma_f32_16x16x32_bf16 v[68:71], v[160:163], v[208:211], v[68:71]
	v_mfma_f32_16x16x32_bf16 v[64:67], v[168:171], v[208:211], v[64:67]
	s_setprio 0
	s_barrier
	s_add_i32 s22, s42, s25
	v_lshl_add_u64 v[188:189], v[188:189], 0, s[4:5]
	s_mov_b32 m0, s22
	ds_read_b128 v[172:175], v195 offset:49152
	ds_read_b128 v[176:179], v195 offset:50176
	ds_read_b128 v[180:183], v195 offset:51200
	ds_read_b128 v[184:187], v195 offset:52224
	ds_read_b128 v[196:199], v195 offset:53248
	ds_read_b128 v[200:203], v195 offset:54272
	ds_read_b128 v[204:207], v195 offset:55296
	ds_read_b128 v[208:211], v195 offset:56320
	global_load_lds_dwordx4 v[188:189], off
	s_add_i32 m0, s22, 0x2000
	s_add_u32 s20, s20, 0x100080
	v_lshl_add_u64 v[188:189], v[212:213], 0, s[4:5]
	s_addc_u32 s21, s21, 0
	s_add_i32 s22, s43, s25
	global_load_lds_dwordx4 v[188:189], off
	v_lshl_add_u64 v[188:189], s[20:21], 0, v[128:129]
	s_mov_b32 m0, s22
	s_nop 0
	global_load_lds_dwordx4 v[188:189], off
	v_lshl_add_u64 v[188:189], s[20:21], 0, v[130:131]
	s_add_i32 m0, s22, 0x2000
	s_nop 0
	global_load_lds_dwordx4 v[188:189], off
	v_lshl_add_u64 v[188:189], v[214:215], 0, s[4:5]
	s_mov_b32 m0, s30
	s_nop 0
	global_load_lds_dwordx4 v[188:189], off
	v_lshl_add_u64 v[188:189], v[216:217], 0, s[4:5]
	s_mov_b32 m0, s31
	s_nop 0
	global_load_lds_dwordx4 v[188:189], off
	s_waitcnt vmcnt(8)
	s_waitcnt lgkmcnt(0)
	s_barrier
	s_setprio 1
	s_waitcnt lgkmcnt(0)
	v_mfma_f32_16x16x32_bf16 v[60:63], v[140:143], v[172:175], v[60:63]
	v_mfma_f32_16x16x32_bf16 v[56:59], v[148:151], v[172:175], v[56:59]
	v_mfma_f32_16x16x32_bf16 v[48:51], v[140:143], v[180:183], v[48:51]
	v_mfma_f32_16x16x32_bf16 v[40:43], v[148:151], v[180:183], v[40:43]
	v_mfma_f32_16x16x32_bf16 v[32:35], v[140:143], v[196:199], v[32:35]
	v_mfma_f32_16x16x32_bf16 v[24:27], v[148:151], v[196:199], v[24:27]
	v_mfma_f32_16x16x32_bf16 v[16:19], v[140:143], v[204:207], v[16:19]
	v_mfma_f32_16x16x32_bf16 v[8:11], v[148:151], v[204:207], v[8:11]
	v_mfma_f32_16x16x32_bf16 v[60:63], v[144:147], v[176:179], v[60:63]
	v_mfma_f32_16x16x32_bf16 v[56:59], v[152:155], v[176:179], v[56:59]
	v_mfma_f32_16x16x32_bf16 v[48:51], v[144:147], v[184:187], v[48:51]
	v_mfma_f32_16x16x32_bf16 v[40:43], v[152:155], v[184:187], v[40:43]
	v_mfma_f32_16x16x32_bf16 v[32:35], v[144:147], v[200:203], v[32:35]
	v_mfma_f32_16x16x32_bf16 v[24:27], v[152:155], v[200:203], v[24:27]
	v_mfma_f32_16x16x32_bf16 v[16:19], v[144:147], v[208:211], v[16:19]
	v_mfma_f32_16x16x32_bf16 v[8:11], v[152:155], v[208:211], v[8:11]
	s_setprio 0
	s_setprio 1
	v_mfma_f32_16x16x32_bf16 v[52:55], v[156:159], v[172:175], v[52:55]
	v_mfma_f32_16x16x32_bf16 v[44:47], v[164:167], v[172:175], v[44:47]
	v_mfma_f32_16x16x32_bf16 v[36:39], v[156:159], v[180:183], v[36:39]
	v_mfma_f32_16x16x32_bf16 v[28:31], v[164:167], v[180:183], v[28:31]
	v_mfma_f32_16x16x32_bf16 v[20:23], v[156:159], v[196:199], v[20:23]
	v_mfma_f32_16x16x32_bf16 v[12:15], v[164:167], v[196:199], v[12:15]
	v_mfma_f32_16x16x32_bf16 v[4:7], v[156:159], v[204:207], v[4:7]
	v_mfma_f32_16x16x32_bf16 v[0:3], v[164:167], v[204:207], v[0:3]
	v_mfma_f32_16x16x32_bf16 v[52:55], v[160:163], v[176:179], v[52:55]
	v_mfma_f32_16x16x32_bf16 v[44:47], v[168:171], v[176:179], v[44:47]
	v_mfma_f32_16x16x32_bf16 v[36:39], v[160:163], v[184:187], v[36:39]
	v_mfma_f32_16x16x32_bf16 v[28:31], v[168:171], v[184:187], v[28:31]
	v_mfma_f32_16x16x32_bf16 v[20:23], v[160:163], v[200:203], v[20:23]
	v_mfma_f32_16x16x32_bf16 v[12:15], v[168:171], v[200:203], v[12:15]
	v_mfma_f32_16x16x32_bf16 v[4:7], v[160:163], v[208:211], v[4:7]
	v_mfma_f32_16x16x32_bf16 v[0:3], v[168:171], v[208:211], v[0:3]
	s_setprio 0
	s_barrier
	s_add_i32 s41, s41, 2
	s_add_u32 s18, s18, 0x100
	s_addc_u32 s19, s19, 0
	s_add_u32 s39, s39, 0x100
	s_addc_u32 s40, s40, 0
	s_cmp_gt_u32 s41, 61
	s_cbranch_scc0 .LBB0_1070
	s_and_b64 vcc, exec, s[6:7]
	s_cbranch_vccz .LBB0_1073
	s_barrier
